# in-proj / ffn_in per-unit header: closed-form tile decode for the launched 256-workgroup grid (general decode kept for other grids), on top of previous
# baseline (speedup 1.0000x reference)
;     __device__ bool next(int i, Unit& u) const {
;         const int ti = i / nseg; u.seg = i - ti * nseg;
;         const long L = (long)ti * G + c; if (L >= nwg) return false;
;         int wgid = (int)L; { const int q = nwg / NXCD, r = nwg % NXCD, xcd = wgid % NXCD, off = wgid / NXCD; wgid = (xcd < r ? xcd * (q + 1) : r * (q + 1) + (xcd - r) * q) + off; }
;         const int nig = WGM * nN, gid = wgid / nig, fm = gid * WGM, gsz = (nM - fm) < WGM ? (nM - fm) : WGM;
;         u.pm = fm + ((wgid % nig) % gsz); u.pn = (wgid % nig) / gsz; return true;
;     }
; template <class Epi, bool ALIGN_EPI, bool SP2, class Hook>
; __device__ __forceinline__ void gemm_phase(LAS unsigned char* lds, const Gemm g, const StaticOrder& S, const Epi& E, Acc& acc, const bool fresh, const Hook& H, const int wave_id) {
;     ...
;         const bool has_next = S.next(ui + 1, nxt);
.LBB0_384:
	s_add_i32 s64, s64, 1
	v_readlane_b32 s2, v249, 2
	v_readlane_b32 s3, v253, 19
	s_mov_b32 s65, s67
	s_cmpk_lg_i32 s2, 0x100
	s_cbranch_scc1 .Lfd_gen_0
	s_lshl_b32 s2, s64, 8
	s_add_i32 s2, s2, s3
	s_cmpk_lt_i32 s2, 0x5c0
	s_cselect_b64 s[0:1], exec, 0
	s_cbranch_scc0 .LBB0_386
	s_lshr_b32 s66, s3, 6
	s_lshl_b32 s2, s64, 2
	s_add_i32 s66, s66, s2
	s_and_b32 s2, s3, 7
	s_lshl_b32 s2, s2, 3
	s_bfe_u32 s3, s3, 0x30003
	s_add_i32 s67, s2, s3
	s_branch .LBB0_386
.Lfd_gen_0:
	v_readlane_b32 s0, v254, 16
	v_readlane_b32 s2, v249, 2
	s_mul_i32 s0, s64, s0
	s_mul_hi_u32 s1, s64, s2
	s_add_i32 s1, s1, s0
	s_mul_i32 s0, s64, s2
	v_readlane_b32 s2, v253, 19
	v_readlane_b32 s3, v253, 20
	s_add_u32 s2, s0, s2
	v_readlane_b32 s0, v250, 7
	s_addc_u32 s3, s1, s0
	v_cmp_gt_i64_e32 vcc, s[2:3], v[236:237]
	s_mov_b32 s65, s67
	v_cmp_lt_i64_e64 s[0:1], s[2:3], v[234:235]
	s_cbranch_vccnz .LBB0_386
	s_ashr_i32 s3, s2, 31
	s_lshr_b32 s3, s3, 29
	s_add_i32 s3, s2, s3
	s_ashr_i32 s4, s3, 3
	s_and_b32 s3, s3, -8
	s_sub_i32 s2, s2, s3
	s_cmp_lt_i32 s2, 0
	s_movk_i32 s3, 0xb9
	s_cselect_b32 s3, s3, 0xb8
	s_mul_i32 s2, s2, s3
	s_add_i32 s2, s2, s4
	s_mul_hi_i32 s3, s2, 0xb21642c9
	s_add_i32 s3, s3, s2
	s_lshr_b32 s4, s3, 31
	s_ashr_i32 s3, s3, 7
	s_add_i32 s3, s3, s4
	s_lshl_b32 s4, s3, 3
	s_mulk_i32 s3, 0xb8
	s_sub_i32 s2, s2, s3
	s_abs_i32 s3, s2
	s_lshr_b32 s66, s2, 3
	s_and_b32 s2, s2, 7
	s_add_i32 s67, s4, s2

;     __device__ bool next(int i, Unit& u) const {
;         const int ti = i / nseg; u.seg = i - ti * nseg;
;         const long L = (long)ti * G + c; if (L >= nwg) return false;
;         int wgid = (int)L; { const int q = nwg / NXCD, r = nwg % NXCD, xcd = wgid % NXCD, off = wgid / NXCD; wgid = (xcd < r ? xcd * (q + 1) : r * (q + 1) + (xcd - r) * q) + off; }
;         const int nig = WGM * nN, gid = wgid / nig, fm = gid * WGM, gsz = (nM - fm) < WGM ? (nM - fm) : WGM;
;         u.pm = fm + ((wgid % nig) % gsz); u.pn = (wgid % nig) / gsz; return true;
;     }
; template <class Epi, bool ALIGN_EPI, bool SP2, class Hook>
; __device__ __forceinline__ void gemm_phase(LAS unsigned char* lds, const Gemm g, const StaticOrder& S, const Epi& E, Acc& acc, const bool fresh, const Hook& H, const int wave_id) {
;     ...
;         const bool has_next = S.next(ui + 1, nxt);
.LBB0_1454:
	s_add_i32 s30, s30, 1
	v_readlane_b32 s2, v249, 2
	v_readlane_b32 s3, v253, 19
	s_mov_b32 s31, s35
	s_cmpk_lg_i32 s2, 0x100
	s_cbranch_scc1 .Lfd_gen_1
	s_lshl_b32 s2, s30, 8
	s_add_i32 s2, s2, s3
	s_cmpk_lt_i32 s2, 0x580
	s_cselect_b64 s[4:5], exec, 0
	s_cbranch_scc0 .LBB0_1456
	s_lshr_b32 s34, s3, 6
	s_lshl_b32 s2, s30, 2
	s_add_i32 s34, s34, s2
	s_and_b32 s2, s3, 7
	s_lshl_b32 s2, s2, 3
	s_bfe_u32 s3, s3, 0x30003
	s_add_i32 s35, s2, s3
	s_branch .LBB0_1456
.Lfd_gen_1:
	v_readlane_b32 s2, v254, 16
	v_readlane_b32 s4, v249, 2
	s_mul_i32 s2, s30, s2
	s_mul_hi_u32 s3, s30, s4
	s_add_i32 s3, s3, s2
	s_mul_i32 s2, s30, s4
	v_readlane_b32 s4, v253, 19
	s_add_u32 s2, s2, s4
	v_readlane_b32 s4, v250, 7
	v_readlane_b32 s5, v253, 20
	s_addc_u32 s3, s3, s4
	v_mov_b64_e32 v[2:3], 0x580
	v_cmp_lt_i64_e64 s[4:5], s[2:3], v[2:3]
	v_mov_b64_e32 v[2:3], 0x57f
	v_cmp_gt_i64_e32 vcc, s[2:3], v[2:3]
	s_mov_b32 s31, s35
	s_cbranch_vccnz .LBB0_1456
	s_ashr_i32 s3, s2, 31
	s_lshr_b32 s3, s3, 29
	s_add_i32 s3, s2, s3
	s_ashr_i32 s6, s3, 3
	s_and_b32 s3, s3, -8
	s_sub_i32 s2, s2, s3
	s_cmp_lt_i32 s2, 0
	s_movk_i32 s3, 0xb1
	s_cselect_b32 s3, s3, 0xb0
	s_mul_i32 s2, s2, s3
	s_add_i32 s2, s2, s6
	s_mul_hi_i32 s3, s2, 0x2e8ba2e9
	s_lshr_b32 s6, s3, 31
	s_ashr_i32 s3, s3, 5
	s_add_i32 s3, s3, s6
	s_lshl_b32 s6, s3, 3
	s_mulk_i32 s3, 0xb0
	s_sub_i32 s2, s2, s3
	s_abs_i32 s3, s2
	s_lshr_b32 s34, s2, 3
	s_and_b32 s2, s2, 7
	s_add_i32 s35, s6, s2
